# combined: early-invalidate + generation broadcast + pool through LDS + mem loop loads together
# speedup vs baseline: 1.0082x; 1.0082x over previous
; __device__ __forceinline__ unsigned xb_add(unsigned* p, unsigned v) { return __hip_atomic_fetch_add(p, v, __ATOMIC_RELAXED, __HIP_MEMORY_SCOPE_AGENT); }
; __device__ __forceinline__ void xcd_barrier(const XcdBarrier& b) {
;     ...
;             __builtin_amdgcn_fence(__ATOMIC_ACQUIRE, "agent");
;             xb_add(&bar[XB_XGEN(b.x)], 1u);
;             asm volatile("s_waitcnt vmcnt(0)" ::: "memory");
.LBB0_474:
	s_or_b64 exec, exec, s[4:5]
	v_readlane_b32 s4, v245, 50
	v_readlane_b32 s5, v245, 51
	s_waitcnt vmcnt(0)
	s_nop 2
	s_waitcnt vmcnt(0)

; __device__ __forceinline__ unsigned xb_ld(unsigned* p)              { return __hip_atomic_load(p, __ATOMIC_RELAXED, __HIP_MEMORY_SCOPE_AGENT); }
; __device__ __forceinline__ unsigned xb_add(unsigned* p, unsigned v) { return __hip_atomic_fetch_add(p, v, __ATOMIC_RELAXED, __HIP_MEMORY_SCOPE_AGENT); }
; #define XB_SPIN(cond, bar) do { unsigned _sp = 0; while (cond) { __builtin_amdgcn_s_sleep(1); \
;     if ((++_sp & 255u) == 0u) { if (xb_ld(&(bar)[XB_TMO])) break; if (_sp > XB_SPIN_CAP) { atomicAdd(&(bar)[XB_TMO], 1u); break; } } } } while (0)
; __device__ __forceinline__ void xcd_barrier(const XcdBarrier& b) {
;     ...
;         const unsigned old = xb_add(&bar[XB_XSUB(b.x)], 1u);
;         const unsigned gen = old / nloc;
;         if (old + 1u == (gen + 1u) * nloc) {
;             __builtin_amdgcn_fence(__ATOMIC_RELEASE, "agent");
;             asm volatile("s_waitcnt vmcnt(0)" ::: "memory");
;             const unsigned og = xb_add(&bar[XB_TOP], 1u);
;             const unsigned tg = og / nx;
;             if (og + 1u == (tg + 1u) * nx) xb_add(&bar[XB_TOPGEN], 1u);
;             else XB_SPIN(xb_ld(&bar[XB_TOPGEN]) == tg, bar);
;             __builtin_amdgcn_fence(__ATOMIC_ACQUIRE, "agent");
;             xb_add(&bar[XB_XGEN(b.x)], 1u);
.LBB0_570:
	s_or_b64 exec, exec, s[6:7]
	s_waitcnt vmcnt(0)
	v_readfirstlane_b32 s4, v5
	v_sub_u32_e32 v6, 0, v4
	s_mov_b64 s[6:7], -1
	v_add_u32_e32 v5, s4, v2
	v_cvt_f32_u32_e32 v2, v4
	v_readlane_b32 s4, v245, 54
	v_readlane_b32 s5, v245, 55
	v_rcp_iflag_f32_e32 v2, v2
	s_nop 0
	v_mul_f32_e32 v2, 0x4f7ffffe, v2
	v_cvt_u32_f32_e32 v2, v2
	v_mul_lo_u32 v6, v6, v2
	v_mul_hi_u32 v6, v2, v6
	v_add_u32_e32 v2, v2, v6
	v_mul_hi_u32 v2, v5, v2
	v_mul_lo_u32 v6, v2, v4
	v_sub_u32_e32 v6, v5, v6
	v_cmp_ge_u32_e32 vcc, v6, v4
	v_add_u32_e32 v7, 1, v2
	v_add_u32_e32 v5, 1, v5
	v_cndmask_b32_e32 v2, v2, v7, vcc
	v_sub_u32_e32 v7, v6, v4
	v_cndmask_b32_e32 v6, v6, v7, vcc
	v_cmp_ge_u32_e32 vcc, v6, v4
	v_add_u32_e32 v6, 1, v2
	s_nop 0
	v_cndmask_b32_e32 v2, v2, v6, vcc
	v_mul_lo_u32 v6, v4, v2
	v_add_u32_e32 v4, v6, v4
	v_cmp_ne_u32_e32 vcc, v5, v4
	v_mov_b64_e32 v[4:5], s[4:5]
	s_cbranch_vccnz .Lxg_skip_L0
	s_add_u32 s14, s4, 0xffffef00
	s_addc_u32 s15, s5, -1
	s_nop 0
	global_atomic_add v3, v213, s[14:15]
	global_atomic_add v3, v213, s[14:15] offset:256
	global_atomic_add v3, v213, s[14:15] offset:512
	global_atomic_add v3, v213, s[14:15] offset:768
	global_atomic_add v3, v213, s[14:15] offset:1024
	global_atomic_add v3, v213, s[14:15] offset:1280
	global_atomic_add v3, v213, s[14:15] offset:1536
	global_atomic_add v3, v213, s[14:15] offset:1792
	global_atomic_add v3, v213, s[14:15] offset:2048
	global_atomic_add v3, v213, s[14:15] offset:2304
	global_atomic_add v3, v213, s[14:15] offset:2560
	global_atomic_add v3, v213, s[14:15] offset:2816
	global_atomic_add v3, v213, s[14:15] offset:3072
	global_atomic_add v3, v213, s[14:15] offset:3328
	global_atomic_add v3, v213, s[14:15] offset:3584
	global_atomic_add v3, v213, s[14:15] offset:3840
.Lxg_skip_L0:
	s_and_saveexec_b64 s[4:5], vcc
	s_cbranch_execz .LBB0_582
	v_readlane_b32 s6, v245, 54
	v_readlane_b32 s7, v245, 55
	s_mov_b64 s[14:15], 0
	s_nop 3
	global_load_dword v4, v3, s[6:7] sc1
	s_waitcnt vmcnt(0)
	v_cmp_eq_u32_e32 vcc, v4, v2
	s_and_saveexec_b64 s[6:7], vcc
	s_cbranch_execz .LBB0_581
	s_mov_b32 s25, 1
	s_branch .LBB0_574

; __device__ __forceinline__ unsigned xb_ld(unsigned* p)              { return __hip_atomic_load(p, __ATOMIC_RELAXED, __HIP_MEMORY_SCOPE_AGENT); }
; __device__ __forceinline__ unsigned xb_add(unsigned* p, unsigned v) { return __hip_atomic_fetch_add(p, v, __ATOMIC_RELAXED, __HIP_MEMORY_SCOPE_AGENT); }
; #define XB_SPIN(cond, bar) do { unsigned _sp = 0; while (cond) { __builtin_amdgcn_s_sleep(1); \
;     if ((++_sp & 255u) == 0u) { if (xb_ld(&(bar)[XB_TMO])) break; if (_sp > XB_SPIN_CAP) { atomicAdd(&(bar)[XB_TMO], 1u); break; } } } } while (0)
; __device__ __forceinline__ void xcd_barrier(const XcdBarrier& b) {
;     ...
;             const unsigned og = xb_add(&bar[XB_TOP], 1u);
;             const unsigned tg = og / nx;
;             if (og + 1u == (tg + 1u) * nx) xb_add(&bar[XB_TOPGEN], 1u);
;             else XB_SPIN(xb_ld(&bar[XB_TOPGEN]) == tg, bar);
.Lxg_skip_L9:
	s_and_saveexec_b64 s[4:5], vcc
	s_cbranch_execz .LBB0_2357
	v_readlane_b32 s6, v245, 54
	v_readlane_b32 s7, v245, 55
	s_mov_b64 s[14:15], 0
	s_nop 3
	global_load_dword v4, v3, s[6:7] sc1
	s_waitcnt vmcnt(0)
	v_cmp_eq_u32_e32 vcc, v4, v2
	s_and_saveexec_b64 s[6:7], vcc
	s_cbranch_execz .LBB0_2356
	s_mov_b32 s24, 1
	s_branch .LBB0_2349
